# gemm1 epilogue: the 16-lane max reduction (xor 1,2,4,8) via v_mov_b32_dpp instead of ds_bpermute; no ds_bpermute left in gemm1
# baseline (speedup 1.0000x reference)
.LBB0_658:
	v_mul_f32_e32 v0, v75, v75
	v_mul_f32_e32 v67, v67, v67
	v_fmac_f32_e32 v0, v74, v74
	v_fmac_f32_e32 v67, v66, v66
	v_fmac_f32_e32 v0, v76, v76
	v_fmac_f32_e32 v67, v68, v68
	v_fmac_f32_e32 v0, v77, v77
	v_fmac_f32_e32 v67, v69, v69
	v_fmac_f32_e32 v0, v70, v70
	v_fmac_f32_e32 v67, v78, v78
	v_fmac_f32_e32 v0, v71, v71
	v_fmac_f32_e32 v67, v79, v79
	v_fmac_f32_e32 v0, v72, v72
	v_fmac_f32_e32 v67, v80, v80
	v_cmp_lt_i32_e32 vcc, v185, v183
	v_fmac_f32_e32 v0, v73, v73
	v_fmac_f32_e32 v67, v81, v81
	v_cndmask_b32_e32 v66, v182, v185, vcc
	v_add_f32_e32 v0, v0, v67
	v_lshlrev_b32_e32 v66, 2, v66
	v_mov_b32_e32 v66, v0
	s_nop 1
	v_permlane16_swap_b32_e32 v0, v66
	v_cmp_lt_i32_e32 vcc, v184, v183
	s_waitcnt lgkmcnt(0)
	v_add_f32_e32 v0, v0, v66
	v_cndmask_b32_e32 v66, v182, v184, vcc
	v_lshlrev_b32_e32 v66, 2, v66
	v_mov_b32_e32 v66, v0
	s_nop 1
	v_permlane32_swap_b32_e32 v0, v66
	s_waitcnt lgkmcnt(0)
	v_add_f32_e32 v0, v0, v66
	v_max_f32_e32 v66, v122, v122
	v_max_f32_e32 v0, v66, v0
	v_xor_b32_e32 v66, 1, v182
	v_cmp_lt_i32_e32 vcc, v66, v183
	s_nop 1
	v_cndmask_b32_e32 v66, v182, v66, vcc
	v_lshlrev_b32_e32 v66, 2, v66
	v_mov_b32_dpp v66, v0 quad_perm:[1,0,3,2] row_mask:0xf bank_mask:0xf
	s_waitcnt lgkmcnt(0)
	v_max_f32_e32 v66, v66, v66
	v_max_f32_e32 v0, v0, v66
	v_xor_b32_e32 v66, 2, v182
	v_cmp_lt_i32_e32 vcc, v66, v183
	s_nop 1
	v_cndmask_b32_e32 v66, v182, v66, vcc
	v_lshlrev_b32_e32 v66, 2, v66
	v_mov_b32_dpp v66, v0 quad_perm:[2,3,0,1] row_mask:0xf bank_mask:0xf
	s_waitcnt lgkmcnt(0)
	v_max_f32_e32 v66, v66, v66
	v_max_f32_e32 v0, v0, v66
	v_xor_b32_e32 v66, 4, v182
	v_cmp_lt_i32_e32 vcc, v66, v183
	s_nop 1
	v_cndmask_b32_e32 v66, v182, v66, vcc
	v_lshlrev_b32_e32 v66, 2, v66
	v_mov_b32_dpp v66, v0 row_ror:4 row_mask:0xf bank_mask:0xf
	s_waitcnt lgkmcnt(0)
	v_max_f32_e32 v66, v66, v66
	v_max_f32_e32 v0, v0, v66
	v_xor_b32_e32 v66, 8, v182
	v_cmp_lt_i32_e32 vcc, v66, v183
	s_nop 1
	v_cndmask_b32_e32 v66, v182, v66, vcc
	v_lshlrev_b32_e32 v66, 2, v66
	v_mov_b32_dpp v66, v0 row_ror:8 row_mask:0xf bank_mask:0xf
	s_and_saveexec_b64 s[28:29], s[38:39]
	s_cbranch_execz .LBB0_663
	s_waitcnt lgkmcnt(0)
	v_max_f32_e32 v66, v66, v66
	v_max_f32_e32 v0, v0, v0
	v_max_f32_e32 v0, v0, v66
	v_mul_f32_e32 v66, 0x3d053526, v0
	v_cndmask_b32_e64 v0, v0, v66, s[40:41]
	s_mov_b32 s9, 0
	s_mov_b64 s[40:41], exec
